# GU SwiGLU epilogue rewritten by hand: packed f32 scale/add, 4 element chains interleaved per store, no s_nop, address by 64-bit add instead of mad (476 -> 322 instrs), bit-exact math
# baseline (speedup 1.0000x reference)
.LBB0_849:
	s_mov_b32 s98, 0xbfb8aa3b
	s_mov_b32 s99, 0xbfb8aa3b
	s_mov_b32 s101, 0
	v_lshl_add_u32 v156, s74, 8, v144
	v_lshl_or_b32 v142, s60, 7, v146
	v_mov_b64_e32 v[140:141], s[6:7]
	v_ashrrev_i32_e32 v143, 31, v142
	v_mad_i64_i32 v[148:149], s[28:29], v156, s64, v[140:141]
	v_lshlrev_b64 v[142:143], 1, v[142:143]
	s_andn2_b64 vcc, exec, s[2:3]
	v_lshl_add_u64 v[148:149], v[148:149], 0, v[142:143]
	v_pk_mul_f32 v[222:223], v[126:127], s[98:99]
	v_pk_mul_f32 v[224:225], v[128:129], s[98:99]
	v_pk_mul_f32 v[226:227], v[118:119], s[98:99]
	v_pk_mul_f32 v[228:229], v[120:121], s[98:99]
	v_exp_f32_e32 v222, v222
	v_exp_f32_e32 v223, v223
	v_exp_f32_e32 v224, v224
	v_exp_f32_e32 v225, v225
	v_exp_f32_e32 v226, v226
	v_exp_f32_e32 v227, v227
	v_exp_f32_e32 v228, v228
	v_exp_f32_e32 v229, v229
	v_pk_add_f32 v[222:223], v[222:223], 1.0 op_sel_hi:[1,0]
	v_pk_add_f32 v[224:225], v[224:225], 1.0 op_sel_hi:[1,0]
	v_pk_add_f32 v[226:227], v[226:227], 1.0 op_sel_hi:[1,0]
	v_pk_add_f32 v[228:229], v[228:229], 1.0 op_sel_hi:[1,0]
	v_rcp_f32_e32 v222, v222
	v_rcp_f32_e32 v223, v223
	v_rcp_f32_e32 v224, v224
	v_rcp_f32_e32 v225, v225
	v_rcp_f32_e32 v226, v226
	v_rcp_f32_e32 v227, v227
	v_rcp_f32_e32 v228, v228
	v_rcp_f32_e32 v229, v229
	v_pk_mul_f32 v[126:127], v[126:127], v[222:223]
	v_pk_mul_f32 v[128:129], v[128:129], v[224:225]
	v_pk_mul_f32 v[118:119], v[118:119], v[226:227]
	v_pk_mul_f32 v[120:121], v[120:121], v[228:229]
	v_pk_mul_f32 v[126:127], v[126:127], v[122:123]
	v_pk_mul_f32 v[128:129], v[128:129], v[124:125]
	v_pk_mul_f32 v[118:119], v[118:119], v[114:115]
	v_pk_mul_f32 v[120:121], v[120:121], v[116:117]
	v_cvt_pk_bf16_f32 v122, v126, v127
	v_cvt_pk_bf16_f32 v123, v128, v129
	v_cvt_pk_bf16_f32 v124, v118, v119
	v_cvt_pk_bf16_f32 v125, v120, v121
	global_store_dwordx4 v[148:149], v[122:125], off
	v_pk_mul_f32 v[230:231], v[110:111], s[98:99]
	v_pk_mul_f32 v[232:233], v[112:113], s[98:99]
	v_pk_mul_f32 v[234:235], v[102:103], s[98:99]
	v_pk_mul_f32 v[236:237], v[104:105], s[98:99]
	s_mov_b32 s100, 0x16000
	v_exp_f32_e32 v230, v230
	v_exp_f32_e32 v231, v231
	v_exp_f32_e32 v232, v232
	v_exp_f32_e32 v233, v233
	v_exp_f32_e32 v234, v234
	v_exp_f32_e32 v235, v235
	v_exp_f32_e32 v236, v236
	v_exp_f32_e32 v237, v237
	v_lshl_add_u64 v[238:239], v[148:149], 0, s[100:101]
	v_pk_add_f32 v[230:231], v[230:231], 1.0 op_sel_hi:[1,0]
	v_pk_add_f32 v[232:233], v[232:233], 1.0 op_sel_hi:[1,0]
	v_pk_add_f32 v[234:235], v[234:235], 1.0 op_sel_hi:[1,0]
	v_pk_add_f32 v[236:237], v[236:237], 1.0 op_sel_hi:[1,0]
	v_rcp_f32_e32 v230, v230
	v_rcp_f32_e32 v231, v231
	v_rcp_f32_e32 v232, v232
	v_rcp_f32_e32 v233, v233
	v_rcp_f32_e32 v234, v234
	v_rcp_f32_e32 v235, v235
	v_rcp_f32_e32 v236, v236
	v_rcp_f32_e32 v237, v237
	v_pk_mul_f32 v[110:111], v[110:111], v[230:231]
	v_pk_mul_f32 v[112:113], v[112:113], v[232:233]
	v_pk_mul_f32 v[102:103], v[102:103], v[234:235]
	v_pk_mul_f32 v[104:105], v[104:105], v[236:237]
	v_pk_mul_f32 v[110:111], v[110:111], v[106:107]
	v_pk_mul_f32 v[112:113], v[112:113], v[108:109]
	v_pk_mul_f32 v[102:103], v[102:103], v[98:99]
	v_pk_mul_f32 v[104:105], v[104:105], v[100:101]
	v_cvt_pk_bf16_f32 v106, v110, v111
	v_cvt_pk_bf16_f32 v107, v112, v113
	v_cvt_pk_bf16_f32 v108, v102, v103
	v_cvt_pk_bf16_f32 v109, v104, v105
	global_store_dwordx4 v[238:239], v[106:109], off
	v_pk_mul_f32 v[222:223], v[94:95], s[98:99]
	v_pk_mul_f32 v[224:225], v[96:97], s[98:99]
	v_pk_mul_f32 v[226:227], v[86:87], s[98:99]
	v_pk_mul_f32 v[228:229], v[88:89], s[98:99]
	s_mov_b32 s100, 0x2c000
	v_exp_f32_e32 v222, v222
	v_exp_f32_e32 v223, v223
	v_exp_f32_e32 v224, v224
	v_exp_f32_e32 v225, v225
	v_exp_f32_e32 v226, v226
	v_exp_f32_e32 v227, v227
	v_exp_f32_e32 v228, v228
	v_exp_f32_e32 v229, v229
	v_lshl_add_u64 v[150:151], v[148:149], 0, s[100:101]
	v_pk_add_f32 v[222:223], v[222:223], 1.0 op_sel_hi:[1,0]
	v_pk_add_f32 v[224:225], v[224:225], 1.0 op_sel_hi:[1,0]
	v_pk_add_f32 v[226:227], v[226:227], 1.0 op_sel_hi:[1,0]
	v_pk_add_f32 v[228:229], v[228:229], 1.0 op_sel_hi:[1,0]
	v_rcp_f32_e32 v222, v222
	v_rcp_f32_e32 v223, v223
	v_rcp_f32_e32 v224, v224
	v_rcp_f32_e32 v225, v225
	v_rcp_f32_e32 v226, v226
	v_rcp_f32_e32 v227, v227
	v_rcp_f32_e32 v228, v228
	v_rcp_f32_e32 v229, v229
	v_pk_mul_f32 v[94:95], v[94:95], v[222:223]
	v_pk_mul_f32 v[96:97], v[96:97], v[224:225]
	v_pk_mul_f32 v[86:87], v[86:87], v[226:227]
	v_pk_mul_f32 v[88:89], v[88:89], v[228:229]
	v_pk_mul_f32 v[94:95], v[94:95], v[90:91]
	v_pk_mul_f32 v[96:97], v[96:97], v[92:93]
	v_pk_mul_f32 v[86:87], v[86:87], v[82:83]
	v_pk_mul_f32 v[88:89], v[88:89], v[84:85]
	v_cvt_pk_bf16_f32 v90, v94, v95
	v_cvt_pk_bf16_f32 v91, v96, v97
	v_cvt_pk_bf16_f32 v92, v86, v87
	v_cvt_pk_bf16_f32 v93, v88, v89
	global_store_dwordx4 v[150:151], v[90:93], off
	v_pk_mul_f32 v[230:231], v[78:79], s[98:99]
	v_pk_mul_f32 v[232:233], v[80:81], s[98:99]
	v_pk_mul_f32 v[234:235], v[70:71], s[98:99]
	v_pk_mul_f32 v[236:237], v[72:73], s[98:99]
	s_mov_b32 s100, 0x42000
	v_exp_f32_e32 v230, v230
	v_exp_f32_e32 v231, v231
	v_exp_f32_e32 v232, v232
	v_exp_f32_e32 v233, v233
	v_exp_f32_e32 v234, v234
	v_exp_f32_e32 v235, v235
	v_exp_f32_e32 v236, v236
	v_exp_f32_e32 v237, v237
	v_lshl_add_u64 v[238:239], v[148:149], 0, s[100:101]
	v_pk_add_f32 v[230:231], v[230:231], 1.0 op_sel_hi:[1,0]
	v_pk_add_f32 v[232:233], v[232:233], 1.0 op_sel_hi:[1,0]
	v_pk_add_f32 v[234:235], v[234:235], 1.0 op_sel_hi:[1,0]
	v_pk_add_f32 v[236:237], v[236:237], 1.0 op_sel_hi:[1,0]
	v_rcp_f32_e32 v230, v230
	v_rcp_f32_e32 v231, v231
	v_rcp_f32_e32 v232, v232
	v_rcp_f32_e32 v233, v233
	v_rcp_f32_e32 v234, v234
	v_rcp_f32_e32 v235, v235
	v_rcp_f32_e32 v236, v236
	v_rcp_f32_e32 v237, v237
	v_pk_mul_f32 v[78:79], v[78:79], v[230:231]
	v_pk_mul_f32 v[80:81], v[80:81], v[232:233]
	v_pk_mul_f32 v[70:71], v[70:71], v[234:235]
	v_pk_mul_f32 v[72:73], v[72:73], v[236:237]
	v_pk_mul_f32 v[78:79], v[78:79], v[74:75]
	v_pk_mul_f32 v[80:81], v[80:81], v[76:77]
	v_pk_mul_f32 v[70:71], v[70:71], v[66:67]
	v_pk_mul_f32 v[72:73], v[72:73], v[68:69]
	v_cvt_pk_bf16_f32 v74, v78, v79
	v_cvt_pk_bf16_f32 v75, v80, v81
	v_cvt_pk_bf16_f32 v76, v70, v71
	v_cvt_pk_bf16_f32 v77, v72, v73
	global_store_dwordx4 v[238:239], v[74:77], off
	v_pk_mul_f32 v[222:223], v[62:63], s[98:99]
	v_pk_mul_f32 v[224:225], v[64:65], s[98:99]
	v_pk_mul_f32 v[226:227], v[54:55], s[98:99]
	v_pk_mul_f32 v[228:229], v[56:57], s[98:99]
	s_mov_b32 s100, 0xb0000
	v_exp_f32_e32 v222, v222
	v_exp_f32_e32 v223, v223
	v_exp_f32_e32 v224, v224
	v_exp_f32_e32 v225, v225
	v_exp_f32_e32 v226, v226
	v_exp_f32_e32 v227, v227
	v_exp_f32_e32 v228, v228
	v_exp_f32_e32 v229, v229
	v_lshl_add_u64 v[150:151], v[148:149], 0, s[100:101]
	v_pk_add_f32 v[222:223], v[222:223], 1.0 op_sel_hi:[1,0]
	v_pk_add_f32 v[224:225], v[224:225], 1.0 op_sel_hi:[1,0]
	v_pk_add_f32 v[226:227], v[226:227], 1.0 op_sel_hi:[1,0]
	v_pk_add_f32 v[228:229], v[228:229], 1.0 op_sel_hi:[1,0]
	v_rcp_f32_e32 v222, v222
	v_rcp_f32_e32 v223, v223
	v_rcp_f32_e32 v224, v224
	v_rcp_f32_e32 v225, v225
	v_rcp_f32_e32 v226, v226
	v_rcp_f32_e32 v227, v227
	v_rcp_f32_e32 v228, v228
	v_rcp_f32_e32 v229, v229
	v_pk_mul_f32 v[62:63], v[62:63], v[222:223]
	v_pk_mul_f32 v[64:65], v[64:65], v[224:225]
	v_pk_mul_f32 v[54:55], v[54:55], v[226:227]
	v_pk_mul_f32 v[56:57], v[56:57], v[228:229]
	v_pk_mul_f32 v[62:63], v[62:63], v[58:59]
	v_pk_mul_f32 v[64:65], v[64:65], v[60:61]
	v_pk_mul_f32 v[54:55], v[54:55], v[50:51]
	v_pk_mul_f32 v[56:57], v[56:57], v[52:53]
	v_cvt_pk_bf16_f32 v58, v62, v63
	v_cvt_pk_bf16_f32 v59, v64, v65
	v_cvt_pk_bf16_f32 v60, v54, v55
	v_cvt_pk_bf16_f32 v61, v56, v57
	global_store_dwordx4 v[150:151], v[58:61], off
	v_pk_mul_f32 v[230:231], v[46:47], s[98:99]
	v_pk_mul_f32 v[232:233], v[48:49], s[98:99]
	v_pk_mul_f32 v[234:235], v[38:39], s[98:99]
	v_pk_mul_f32 v[236:237], v[40:41], s[98:99]
	s_mov_b32 s100, 0xc6000
	v_exp_f32_e32 v230, v230
	v_exp_f32_e32 v231, v231
	v_exp_f32_e32 v232, v232
	v_exp_f32_e32 v233, v233
	v_exp_f32_e32 v234, v234
	v_exp_f32_e32 v235, v235
	v_exp_f32_e32 v236, v236
	v_exp_f32_e32 v237, v237
	v_lshl_add_u64 v[238:239], v[148:149], 0, s[100:101]
	v_pk_add_f32 v[230:231], v[230:231], 1.0 op_sel_hi:[1,0]
	v_pk_add_f32 v[232:233], v[232:233], 1.0 op_sel_hi:[1,0]
	v_pk_add_f32 v[234:235], v[234:235], 1.0 op_sel_hi:[1,0]
	v_pk_add_f32 v[236:237], v[236:237], 1.0 op_sel_hi:[1,0]
	v_rcp_f32_e32 v230, v230
	v_rcp_f32_e32 v231, v231
	v_rcp_f32_e32 v232, v232
	v_rcp_f32_e32 v233, v233
	v_rcp_f32_e32 v234, v234
	v_rcp_f32_e32 v235, v235
	v_rcp_f32_e32 v236, v236
	v_rcp_f32_e32 v237, v237
	v_pk_mul_f32 v[46:47], v[46:47], v[230:231]
	v_pk_mul_f32 v[48:49], v[48:49], v[232:233]
	v_pk_mul_f32 v[38:39], v[38:39], v[234:235]
	v_pk_mul_f32 v[40:41], v[40:41], v[236:237]
	v_pk_mul_f32 v[46:47], v[46:47], v[42:43]
	v_pk_mul_f32 v[48:49], v[48:49], v[44:45]
	v_pk_mul_f32 v[38:39], v[38:39], v[34:35]
	v_pk_mul_f32 v[40:41], v[40:41], v[36:37]
	v_cvt_pk_bf16_f32 v42, v46, v47
	v_cvt_pk_bf16_f32 v43, v48, v49
	v_cvt_pk_bf16_f32 v44, v38, v39
	v_cvt_pk_bf16_f32 v45, v40, v41
	global_store_dwordx4 v[238:239], v[42:45], off
	v_pk_mul_f32 v[222:223], v[30:31], s[98:99]
	v_pk_mul_f32 v[224:225], v[32:33], s[98:99]
	v_pk_mul_f32 v[226:227], v[22:23], s[98:99]
	v_pk_mul_f32 v[228:229], v[24:25], s[98:99]
	s_mov_b32 s100, 0xdc000
	v_exp_f32_e32 v222, v222
	v_exp_f32_e32 v223, v223
	v_exp_f32_e32 v224, v224
	v_exp_f32_e32 v225, v225
	v_exp_f32_e32 v226, v226
	v_exp_f32_e32 v227, v227
	v_exp_f32_e32 v228, v228
	v_exp_f32_e32 v229, v229
	v_lshl_add_u64 v[150:151], v[148:149], 0, s[100:101]
	v_pk_add_f32 v[222:223], v[222:223], 1.0 op_sel_hi:[1,0]
	v_pk_add_f32 v[224:225], v[224:225], 1.0 op_sel_hi:[1,0]
	v_pk_add_f32 v[226:227], v[226:227], 1.0 op_sel_hi:[1,0]
	v_pk_add_f32 v[228:229], v[228:229], 1.0 op_sel_hi:[1,0]
	v_rcp_f32_e32 v222, v222
	v_rcp_f32_e32 v223, v223
	v_rcp_f32_e32 v224, v224
	v_rcp_f32_e32 v225, v225
	v_rcp_f32_e32 v226, v226
	v_rcp_f32_e32 v227, v227
	v_rcp_f32_e32 v228, v228
	v_rcp_f32_e32 v229, v229
	v_pk_mul_f32 v[30:31], v[30:31], v[222:223]
	v_pk_mul_f32 v[32:33], v[32:33], v[224:225]
	v_pk_mul_f32 v[22:23], v[22:23], v[226:227]
	v_pk_mul_f32 v[24:25], v[24:25], v[228:229]
	v_pk_mul_f32 v[30:31], v[30:31], v[26:27]
	v_pk_mul_f32 v[32:33], v[32:33], v[28:29]
	v_pk_mul_f32 v[22:23], v[22:23], v[18:19]
	v_pk_mul_f32 v[24:25], v[24:25], v[20:21]
	v_cvt_pk_bf16_f32 v26, v30, v31
	v_cvt_pk_bf16_f32 v27, v32, v33
	v_cvt_pk_bf16_f32 v28, v22, v23
	v_cvt_pk_bf16_f32 v29, v24, v25
	global_store_dwordx4 v[150:151], v[26:29], off
	v_pk_mul_f32 v[230:231], v[14:15], s[98:99]
	v_pk_mul_f32 v[232:233], v[16:17], s[98:99]
	v_pk_mul_f32 v[234:235], v[6:7], s[98:99]
	v_pk_mul_f32 v[236:237], v[8:9], s[98:99]
	s_mov_b32 s100, 0xf2000
	v_exp_f32_e32 v230, v230
	v_exp_f32_e32 v231, v231
	v_exp_f32_e32 v232, v232
	v_exp_f32_e32 v233, v233
	v_exp_f32_e32 v234, v234
	v_exp_f32_e32 v235, v235
	v_exp_f32_e32 v236, v236
	v_exp_f32_e32 v237, v237
	v_lshl_add_u64 v[238:239], v[148:149], 0, s[100:101]
	v_pk_add_f32 v[230:231], v[230:231], 1.0 op_sel_hi:[1,0]
	v_pk_add_f32 v[232:233], v[232:233], 1.0 op_sel_hi:[1,0]
	v_pk_add_f32 v[234:235], v[234:235], 1.0 op_sel_hi:[1,0]
	v_pk_add_f32 v[236:237], v[236:237], 1.0 op_sel_hi:[1,0]
	v_rcp_f32_e32 v230, v230
	v_rcp_f32_e32 v231, v231
	v_rcp_f32_e32 v232, v232
	v_rcp_f32_e32 v233, v233
	v_rcp_f32_e32 v234, v234
	v_rcp_f32_e32 v235, v235
	v_rcp_f32_e32 v236, v236
	v_rcp_f32_e32 v237, v237
	v_pk_mul_f32 v[14:15], v[14:15], v[230:231]
	v_pk_mul_f32 v[16:17], v[16:17], v[232:233]
	v_pk_mul_f32 v[6:7], v[6:7], v[234:235]
	v_pk_mul_f32 v[8:9], v[8:9], v[236:237]
	v_pk_mul_f32 v[14:15], v[14:15], v[10:11]
	v_pk_mul_f32 v[16:17], v[16:17], v[12:13]
	v_pk_mul_f32 v[6:7], v[6:7], v[2:3]
	v_pk_mul_f32 v[8:9], v[8:9], v[4:5]
	v_cvt_pk_bf16_f32 v10, v14, v15
	v_cvt_pk_bf16_f32 v11, v16, v17
	v_cvt_pk_bf16_f32 v12, v6, v7
	v_cvt_pk_bf16_f32 v13, v8, v9
	global_store_dwordx4 v[238:239], v[10:13], off
	s_mov_b64 s[28:29], -1
	s_cbranch_vccnz .LBB0_842
	s_andn2_b64 vcc, exec, s[12:13]
	s_cbranch_vccnz .LBB0_841
	s_barrier
	s_branch .LBB0_841
